# v50 + packed f32 VALU ops (v_pk_mul/add_f32) in the three scan step loops split into single-op pairs (packed f32 beside MFMAs is an anti-lever per docs 7.5)
# speedup vs baseline: 1.0054x; 1.0003x over previous
.LBB0_1113:
	v_lshl_add_u32 v2, s14, 13, v206
	s_andn2_b64 vcc, exec, s[46:47]
	v_lshl_add_u32 v84, s24, 1, v2
	s_cbranch_vccnz .LBB0_1115
	v_add_u32_e32 v85, s25, v84
	v_add_u32_e32 v86, s25, v85
	v_add_u32_e32 v87, s28, v86
	v_add_u32_e32 v88, s25, v87
	v_add_u32_e32 v89, s25, v88
	v_add_u32_e32 v90, s25, v89
	ds_read_u16 v98, v84
	ds_read_u16 v99, v2
	ds_read_u16 v100, v86
	ds_read_u16 v88, v88
	ds_read_u16 v89, v89
	ds_read_u16 v101, v87
	ds_read_u16 v85, v85
	s_waitcnt lgkmcnt(6)
	v_lshlrev_b32_e32 v87, 16, v98
	s_waitcnt lgkmcnt(5)
	v_lshlrev_b32_e32 v86, 16, v99
	v_add_f32_e32 v68, v68, v86
	v_add_f32_e32 v69, v69, v87
	v_add_u32_e32 v91, s28, v90
	s_waitcnt lgkmcnt(0)
	v_lshlrev_b32_e32 v86, 16, v85
	ds_read_u16 v85, v90
	v_lshlrev_b32_e32 v87, 16, v100
	v_add_u32_e32 v92, s25, v91
	v_add_f32_e32 v70, v70, v86
	v_add_f32_e32 v71, v71, v87
	v_lshlrev_b32_e32 v86, 16, v101
	v_lshlrev_b32_e32 v87, 16, v88
	v_add_u32_e32 v93, s25, v92
	v_add_f32_e32 v72, v72, v86
	v_add_f32_e32 v73, v73, v87
	s_waitcnt lgkmcnt(0)
	v_lshlrev_b32_e32 v87, 16, v85
	ds_read_u16 v85, v91
	ds_read_u16 v88, v92
	v_add_u32_e32 v94, s25, v93
	v_lshlrev_b32_e32 v86, 16, v89
	ds_read_u16 v89, v93
	ds_read_u16 v90, v94
	v_add_u32_e32 v95, s28, v94
	v_add_u32_e32 v96, s25, v95
	v_add_u32_e32 v97, s25, v96
	v_add_f32_e32 v74, v74, v86
	v_add_f32_e32 v75, v75, v87
	s_waitcnt lgkmcnt(3)
	v_lshlrev_b32_e32 v86, 16, v85
	s_waitcnt lgkmcnt(2)
	v_lshlrev_b32_e32 v87, 16, v88
	ds_read_u16 v85, v95
	ds_read_u16 v88, v96
	v_add_u32_e32 v102, s25, v97
	v_add_f32_e32 v76, v76, v86
	v_add_f32_e32 v77, v77, v87
	s_waitcnt lgkmcnt(3)
	v_lshlrev_b32_e32 v86, 16, v89
	s_waitcnt lgkmcnt(2)
	v_lshlrev_b32_e32 v87, 16, v90
	ds_read_u16 v89, v97
	ds_read_u16 v90, v102
	v_add_f32_e32 v78, v78, v86
	v_add_f32_e32 v79, v79, v87
	s_waitcnt lgkmcnt(3)
	v_lshlrev_b32_e32 v86, 16, v85
	s_waitcnt lgkmcnt(2)
	v_lshlrev_b32_e32 v87, 16, v88
	v_add_f32_e32 v80, v80, v86
	v_add_f32_e32 v81, v81, v87
	s_waitcnt lgkmcnt(1)
	v_lshlrev_b32_e32 v86, 16, v89
	s_waitcnt lgkmcnt(0)
	v_lshlrev_b32_e32 v87, 16, v90
	v_add_f32_e32 v82, v82, v86
	v_add_f32_e32 v83, v83, v87
.LBB0_1115:
	s_nop 6
	v_cvt_pk_bf16_f32 v68, v68, s0
	ds_write_b16 v2, v68
	v_cvt_pk_bf16_f32 v2, v69, s0
	ds_write_b16 v84, v2
	v_cvt_pk_bf16_f32 v2, v70, s0
	v_add_u32_e32 v68, s25, v84
	ds_write_b16 v68, v2
	v_cvt_pk_bf16_f32 v2, v71, s0
	v_add_u32_e32 v68, s25, v68
	ds_write_b16 v68, v2
	v_cvt_pk_bf16_f32 v2, v72, s0
	v_add_u32_e32 v68, s28, v68
	ds_write_b16 v68, v2
	v_cvt_pk_bf16_f32 v2, v73, s0
	v_add_u32_e32 v68, s25, v68
	ds_write_b16 v68, v2
	v_cvt_pk_bf16_f32 v2, v74, s0
	v_add_u32_e32 v68, s25, v68
	ds_write_b16 v68, v2
	v_cvt_pk_bf16_f32 v2, v75, s0
	v_add_u32_e32 v68, s25, v68
	ds_write_b16 v68, v2
	v_cvt_pk_bf16_f32 v2, v76, s0
	v_add_u32_e32 v68, s28, v68
	ds_write_b16 v68, v2
	v_cvt_pk_bf16_f32 v2, v77, s0
	v_add_u32_e32 v68, s25, v68
	ds_write_b16 v68, v2
	v_cvt_pk_bf16_f32 v2, v78, s0
	v_add_u32_e32 v68, s25, v68
	ds_write_b16 v68, v2
	v_cvt_pk_bf16_f32 v2, v79, s0
	v_add_u32_e32 v68, s25, v68
	ds_write_b16 v68, v2
	v_cvt_pk_bf16_f32 v2, v80, s0
	v_add_u32_e32 v68, s28, v68
	ds_write_b16 v68, v2
	v_cvt_pk_bf16_f32 v2, v81, s0
	v_add_u32_e32 v68, s25, v68
	ds_write_b16 v68, v2
	v_cvt_pk_bf16_f32 v2, v82, s0
	v_add_u32_e32 v68, s25, v68
	ds_write_b16 v68, v2
	v_cvt_pk_bf16_f32 v2, v83, s0
	v_add_u32_e32 v68, s25, v68
	ds_write_b16 v68, v2
	v_add_u32_e32 v2, s18, v203
	ds_read_b128 v[68:71], v2 offset:46432
	ds_read_b128 v[72:75], v2 offset:46400
	ds_read_b128 v[82:85], v2 offset:46368
	ds_read_b128 v[86:89], v2 offset:46336
	s_mov_b64 s[14:15], 0
	s_waitcnt lgkmcnt(3)
	v_mul_f32_e32 v80, v64, v68
	v_mul_f32_e32 v81, v65, v69
	s_waitcnt lgkmcnt(2)
	v_mul_f32_e32 v76, v60, v72
	v_mul_f32_e32 v77, v61, v73
	s_waitcnt lgkmcnt(1)
	v_mul_f32_e32 v72, v56, v82
	v_mul_f32_e32 v73, v57, v83
	v_mul_f32_e32 v82, v66, v70
	v_mul_f32_e32 v83, v67, v71
	v_mul_f32_e32 v78, v62, v74
	v_mul_f32_e32 v79, v63, v75
	v_mul_f32_e32 v74, v58, v84
	v_mul_f32_e32 v75, v59, v85
	s_waitcnt lgkmcnt(0)
	v_mul_f32_e32 v70, v54, v88
	v_mul_f32_e32 v71, v55, v89
	v_mul_f32_e32 v68, v52, v86
	v_mul_f32_e32 v69, v53, v87
	ds_read_b64_tr_b16 v[84:85], v214 offset:25856
	ds_read_b64_tr_b16 v[86:87], v214 offset:27136
	ds_read_b64_tr_b16 v[140:141], v215 offset:36096
	ds_read_b64_tr_b16 v[142:143], v215 offset:37376
	ds_read_b64_tr_b16 v[144:145], v215 offset:41216
	ds_read_b64_tr_b16 v[146:147], v215 offset:42496
	ds_read_b64_tr_b16 v[100:101], v214 offset:25920
	ds_read_b64_tr_b16 v[116:117], v214 offset:25984
	ds_read_b64_tr_b16 v[228:229], v214 offset:26048
	ds_read_b64_tr_b16 v[102:103], v214 offset:27200
	ds_read_b64_tr_b16 v[118:119], v214 offset:27264
	ds_read_b64_tr_b16 v[230:231], v214 offset:27328
	s_waitcnt lgkmcnt(8)
	v_mfma_f32_32x32x16_bf16 v[68:83], v[84:87], v[140:143], v[68:83]
	ds_read_b64_tr_b16 v[84:85], v214 offset:30976
	ds_read_b64_tr_b16 v[86:87], v214 offset:32256
	ds_read_b128 v[104:107], v2 offset:46464
	ds_read_b128 v[88:91], v2 offset:46496
	ds_read_b128 v[92:95], v2 offset:46528
	ds_read_b128 v[96:99], v2 offset:46560
	ds_read_b64_tr_b16 v[108:109], v214 offset:31040
	ds_read_b64_tr_b16 v[120:121], v214 offset:31104
	ds_read_b64_tr_b16 v[232:233], v214 offset:31168
	ds_read_b64_tr_b16 v[110:111], v214 offset:32320
	ds_read_b64_tr_b16 v[122:123], v214 offset:32384
	ds_read_b64_tr_b16 v[234:235], v214 offset:32448
	s_waitcnt lgkmcnt(6)
	v_mul_f32_e32 v96, v48, v96
	v_mul_f32_e32 v97, v49, v97
	v_mul_f32_e32 v92, v44, v92
	v_mul_f32_e32 v93, v45, v93
	v_mul_f32_e32 v88, v40, v88
	v_mul_f32_e32 v89, v41, v89
	v_mul_f32_e32 v98, v50, v98
	v_mul_f32_e32 v99, v51, v99
	v_mul_f32_e32 v94, v46, v94
	v_mul_f32_e32 v95, v47, v95
	v_mul_f32_e32 v90, v42, v90
	v_mul_f32_e32 v91, v43, v91
	v_mfma_f32_32x32x16_bf16 v[68:83], v[84:87], v[144:147], v[68:83]
	v_mul_f32_e64 v86, v38, v106
	v_mul_f32_e64 v87, v39, v107
	v_mul_f32_e64 v84, v36, v104
	v_mul_f32_e64 v85, v37, v105
	s_nop 1
	v_mfma_f32_32x32x16_bf16 v[84:99], v[100:103], v[140:143], v[84:99]
	ds_read_b128 v[100:103], v2 offset:46688
	ds_read_b128 v[104:107], v2 offset:46656
	ds_read_b128 v[124:127], v2 offset:46624
	ds_read_b128 v[128:131], v2 offset:46592
	s_waitcnt lgkmcnt(3)
	v_mul_f32_e32 v112, v32, v100
	v_mul_f32_e32 v113, v33, v101
	v_mul_f32_e32 v114, v34, v102
	v_mul_f32_e32 v115, v35, v103
	s_waitcnt lgkmcnt(0)
	v_mul_f32_e32 v102, v22, v130
	v_mul_f32_e32 v103, v23, v131
	v_mul_f32_e32 v100, v20, v128
	v_mul_f32_e32 v101, v21, v129
	v_mfma_f32_32x32x16_bf16 v[84:99], v[108:111], v[144:147], v[84:99]
	v_mul_f32_e64 v108, v28, v104
	v_mul_f32_e64 v109, v29, v105
	v_mul_f32_e64 v104, v24, v124
	v_mul_f32_e64 v105, v25, v125
	v_mul_f32_e64 v110, v30, v106
	v_mul_f32_e64 v111, v31, v107
	v_mul_f32_e32 v106, v26, v126
	v_mul_f32_e32 v107, v27, v127
	s_nop 1
	v_mfma_f32_32x32x16_bf16 v[100:115], v[116:119], v[140:143], v[100:115]
	ds_read_b128 v[116:119], v2 offset:46816
	ds_read_b128 v[124:127], v2 offset:46784
	ds_read_b128 v[236:239], v2 offset:46752
	ds_read_b128 v[240:243], v2 offset:46720
	s_waitcnt lgkmcnt(3)
	v_mul_f32_e32 v128, v16, v116
	v_mul_f32_e32 v129, v17, v117
	s_waitcnt lgkmcnt(2)
	v_mul_f32_e32 v124, v12, v124
	v_mul_f32_e32 v125, v13, v125
	v_mul_f32_e32 v130, v18, v118
	v_mul_f32_e32 v131, v19, v119
	v_mul_f32_e32 v126, v14, v126
	v_mul_f32_e32 v127, v15, v127
	s_waitcnt lgkmcnt(0)
	v_mul_f32_e32 v118, v6, v242
	v_mul_f32_e32 v119, v7, v243
	v_mfma_f32_32x32x16_bf16 v[100:115], v[120:123], v[144:147], v[100:115]
	v_mul_f32_e64 v120, v8, v236
	v_mul_f32_e64 v121, v9, v237
	v_mul_f32_e64 v122, v10, v238
	v_mul_f32_e64 v123, v11, v239
	v_mul_f32_e64 v116, v4, v240
	v_mul_f32_e64 v117, v5, v241
	s_nop 1
	v_mfma_f32_32x32x16_bf16 v[116:131], v[228:231], v[140:143], v[116:131]
	v_mfma_f32_32x32x16_bf16 v[116:131], v[232:235], v[144:147], v[116:131]
.LBB0_1116:
	s_and_b64 vcc, exec, s[14:15]
	s_cbranch_vccz .LBB0_1108
	s_waitcnt vmcnt(0)
	v_cvt_f32_f16_sdwa v81, v195 dst_sel:DWORD dst_unused:UNUSED_PAD src0_sel:WORD_1
	v_cvt_f32_f16_e32 v80, v195
	v_cvt_f32_f16_sdwa v83, v197 dst_sel:DWORD dst_unused:UNUSED_PAD src0_sel:WORD_1
	v_cvt_f32_f16_e32 v82, v197
	v_cvt_f32_f16_sdwa v85, v199 dst_sel:DWORD dst_unused:UNUSED_PAD src0_sel:WORD_1
	v_cvt_f32_f16_e32 v84, v199
	v_cvt_f32_f16_sdwa v87, v201 dst_sel:DWORD dst_unused:UNUSED_PAD src0_sel:WORD_1
	v_cvt_f32_f16_e32 v86, v201
	v_add_f32_e32 v88, 0, v80
	v_add_f32_e32 v89, 0, v81
	v_cvt_f32_f16_sdwa v97, v205 dst_sel:DWORD dst_unused:UNUSED_PAD src0_sel:WORD_1
	v_cvt_f32_f16_e32 v96, v205
	v_add_f32_e32 v90, v88, v82
	v_add_f32_e32 v91, v89, v83
	v_cvt_f32_f16_sdwa v99, v208 dst_sel:DWORD dst_unused:UNUSED_PAD src0_sel:WORD_1
	v_cvt_f32_f16_e32 v98, v208
	v_add_f32_e32 v92, v90, v84
	v_add_f32_e32 v93, v91, v85
	v_cvt_f32_f16_sdwa v75, v210 dst_sel:DWORD dst_unused:UNUSED_PAD src0_sel:WORD_1
	v_cvt_f32_f16_e32 v74, v210
	v_add_f32_e32 v94, v92, v86
	v_add_f32_e32 v95, v93, v87
	v_cvt_f32_f16_sdwa v69, v226 dst_sel:DWORD dst_unused:UNUSED_PAD src0_sel:WORD_1
	v_cvt_f32_f16_e32 v68, v226
	v_add_f32_e32 v100, v94, v96
	v_add_f32_e32 v101, v95, v97
	v_exp_f32_e32 v80, v80
	v_add_f32_e32 v102, v100, v98
	v_add_f32_e32 v103, v101, v99
	v_exp_f32_e32 v81, v81
	v_add_f32_e32 v104, v102, v74
	v_add_f32_e32 v105, v103, v75
	ds_write_b128 v216, v[136:139] offset:36096
	ds_write_b128 v216, v[132:135] offset:36112
	v_add_f32_e32 v72, v104, v68
	v_add_f32_e32 v73, v105, v69
	ds_bpermute_b32 v70, v224, v72
	ds_bpermute_b32 v71, v224, v73
	ds_bpermute_b32 v76, v224, v72 offset:64
	ds_bpermute_b32 v77, v224, v73 offset:64
	ds_bpermute_b32 v78, v224, v72 offset:128
	ds_bpermute_b32 v79, v224, v73 offset:128
	ds_bpermute_b32 v106, v224, v72 offset:192
	ds_bpermute_b32 v107, v224, v73 offset:192
	s_waitcnt lgkmcnt(6)
	v_cndmask_b32_e64 v109, 0, v71, s[6:7]
	v_cndmask_b32_e64 v108, 0, v70, s[6:7]
	s_waitcnt lgkmcnt(4)
	v_cndmask_b32_e64 v111, 0, v77, s[8:9]
	v_cndmask_b32_e64 v110, 0, v76, s[8:9]
	v_add_f32_e32 v108, v108, v110
	v_add_f32_e32 v109, v109, v111
	s_waitcnt lgkmcnt(2)
	v_cndmask_b32_e64 v111, 0, v79, s[10:11]
	v_cndmask_b32_e64 v110, 0, v78, s[10:11]
	v_add_f32_e32 v108, v108, v110
	v_add_f32_e32 v109, v109, v111
	v_add_f32_e32 v110, v70, v76
	v_add_f32_e32 v111, v71, v77
	v_sub_f32_e32 v80, 1.0, v80
	v_sub_f32_e32 v81, 1.0, v81
	v_add_f32_e32 v70, v110, v78
	v_add_f32_e32 v71, v111, v79
	v_exp_f32_e32 v76, v110
	s_waitcnt lgkmcnt(0)
	v_add_f32_e32 v70, v70, v106
	v_add_f32_e32 v71, v71, v107
	v_sub_f32_e32 v106, v108, v110
	v_sub_f32_e32 v107, v109, v111
	v_exp_f32_e32 v77, v111
	v_add_f32_e32 v88, v88, v106
	v_add_f32_e32 v89, v89, v107
	v_sub_f32_e32 v78, v70, v110
	v_sub_f32_e32 v79, v71, v111
	v_exp_f32_e32 v108, v88
	v_exp_f32_e32 v109, v89
	v_exp_f32_e64 v88, -v88
	v_exp_f32_e64 v89, -v89
	v_exp_f32_e32 v78, v78
	v_exp_f32_e32 v79, v79
	v_lshlrev_b32_e32 v110, 16, v194
	v_and_b32_e32 v111, 0xffff0000, v194
	v_mul_f32_e32 v108, v108, v110
	v_mul_f32_e32 v109, v109, v111
	v_mul_f32_e32 v80, v80, v88
	v_mul_f32_e32 v81, v81, v89
	v_mul_f32_e32 v88, v76, v108
	v_mul_f32_e32 v89, v77, v109
	v_cvt_pk_bf16_f32 v2, v108, v109
	ds_write_b32 v217, v2
	v_cvt_pk_bf16_f32 v2, v88, v89
	v_mul_f32_e32 v110, v78, v80
	v_mul_f32_e32 v111, v79, v81
	ds_write_b32 v218, v2 offset:8704
	v_cvt_pk_bf16_f32 v2, v80, v81
	v_add_f32_e32 v80, v90, v106
	v_add_f32_e32 v81, v91, v107
	v_exp_f32_e32 v82, v82
	v_exp_f32_e32 v83, v83
	v_exp_f32_e32 v88, v80
	v_exp_f32_e32 v89, v81
	v_exp_f32_e64 v80, -v80
	v_exp_f32_e64 v81, -v81
	v_sub_f32_e32 v82, 1.0, v82
	v_sub_f32_e32 v83, 1.0, v83
	v_lshlrev_b32_e32 v90, 16, v196
	v_and_b32_e32 v91, 0xffff0000, v196
	ds_write_b32 v217, v2 offset:17152
	v_cvt_pk_bf16_f32 v2, v110, v111
	v_mul_f32_e32 v88, v88, v90
	v_mul_f32_e32 v89, v89, v91
	v_mul_f32_e32 v80, v82, v80
	v_mul_f32_e32 v81, v83, v81
	ds_write_b32 v219, v2 offset:25856
	v_mul_f32_e32 v82, v76, v88
	v_mul_f32_e32 v83, v77, v89
	v_mul_f32_e32 v90, v78, v80
	v_mul_f32_e32 v91, v79, v81
	v_cvt_pk_bf16_f32 v2, v88, v89
	v_cvt_pk_bf16_f32 v80, v80, v81
	v_cvt_pk_bf16_f32 v82, v82, v83
	ds_write2st64_b32 v220, v2, v80 offset1:67
	v_cvt_pk_bf16_f32 v2, v90, v91
	ds_write_b32 v221, v82 offset:8704
	ds_write_b32 v222, v2 offset:25856
	v_add_f32_e32 v80, v92, v106
	v_add_f32_e32 v81, v93, v107
	v_exp_f32_e32 v84, v84
	v_exp_f32_e32 v85, v85
	v_exp_f32_e32 v82, v80
	v_exp_f32_e32 v83, v81
	v_exp_f32_e64 v80, -v80
	v_exp_f32_e64 v81, -v81
	v_sub_f32_e32 v84, 1.0, v84
	v_sub_f32_e32 v85, 1.0, v85
	v_lshlrev_b32_e32 v88, 16, v198
	v_and_b32_e32 v89, 0xffff0000, v198
	v_mul_f32_e32 v82, v82, v88
	v_mul_f32_e32 v83, v83, v89
	v_mul_f32_e32 v80, v84, v80
	v_mul_f32_e32 v81, v85, v81
	v_mul_f32_e32 v84, v76, v82
	v_mul_f32_e32 v85, v77, v83
	v_mul_f32_e32 v88, v78, v80
	v_mul_f32_e32 v89, v79, v81
	v_cvt_pk_bf16_f32 v91, v80, v81
	v_add_f32_e32 v80, v94, v106
	v_add_f32_e32 v81, v95, v107
	v_cvt_pk_bf16_f32 v2, v82, v83
	v_cvt_pk_bf16_f32 v90, v84, v85
	v_exp_f32_e32 v82, v80
	v_exp_f32_e32 v84, v86
	v_exp_f32_e32 v85, v87
	v_exp_f32_e32 v83, v81
	v_exp_f32_e64 v80, -v80
	v_exp_f32_e64 v81, -v81
	v_lshlrev_b32_e32 v86, 16, v200
	v_and_b32_e32 v87, 0xffff0000, v200
	v_sub_f32_e32 v84, 1.0, v84
	v_sub_f32_e32 v85, 1.0, v85
	v_mul_f32_e32 v82, v82, v86
	v_mul_f32_e32 v83, v83, v87
	v_mul_f32_e32 v80, v84, v80
	v_mul_f32_e32 v81, v85, v81
	v_mul_f32_e32 v84, v76, v82
	v_mul_f32_e32 v85, v77, v83
	v_cvt_pk_bf16_f32 v82, v82, v83
	ds_write2_b32 v220, v2, v82 offset0:68 offset1:136
	v_cvt_pk_bf16_f32 v2, v84, v85
	v_add_u32_e32 v82, 0x2200, v221
	v_cvt_pk_bf16_f32 v88, v88, v89
	v_mul_f32_e32 v86, v78, v80
	v_mul_f32_e32 v87, v79, v81
	ds_write2_b32 v82, v90, v2 offset0:66 offset1:132
	v_cvt_pk_bf16_f32 v2, v80, v81
	v_add_u32_e32 v89, 0x4400, v220
	ds_write2_b32 v89, v91, v2 offset0:4 offset1:72
	v_cvt_pk_bf16_f32 v2, v86, v87
	v_add_u32_e32 v80, 0x6400, v222
	ds_write2_b32 v80, v88, v2 offset0:144 offset1:224
	v_add_f32_e32 v80, v100, v106
	v_add_f32_e32 v81, v101, v107
	v_exp_f32_e32 v84, v96
	v_exp_f32_e32 v85, v97
	v_exp_f32_e32 v82, v80
	v_exp_f32_e32 v83, v81
	v_exp_f32_e64 v80, -v80
	v_exp_f32_e64 v81, -v81
	v_sub_f32_e32 v84, 1.0, v84
	v_sub_f32_e32 v85, 1.0, v85
	v_lshlrev_b32_e32 v86, 16, v202
	v_and_b32_e32 v87, 0xffff0000, v202
	v_mul_f32_e32 v82, v82, v86
	v_mul_f32_e32 v83, v83, v87
	v_mul_f32_e32 v80, v84, v80
	v_mul_f32_e32 v81, v85, v81
	v_mul_f32_e32 v84, v76, v82
	v_mul_f32_e32 v85, v77, v83
	v_mul_f32_e32 v86, v78, v80
	v_mul_f32_e32 v87, v79, v81
	v_cvt_pk_bf16_f32 v90, v80, v81
	v_add_f32_e32 v80, v102, v106
	v_add_f32_e32 v81, v103, v107
	v_cvt_pk_bf16_f32 v2, v82, v83
	v_cvt_pk_bf16_f32 v88, v84, v85
	v_exp_f32_e32 v82, v80
	v_exp_f32_e32 v84, v98
	v_exp_f32_e32 v85, v99
	v_exp_f32_e32 v83, v81
	v_exp_f32_e64 v80, -v80
	v_exp_f32_e64 v81, -v81
	v_cvt_pk_bf16_f32 v91, v86, v87
	v_lshlrev_b32_e32 v86, 16, v207
	v_and_b32_e32 v87, 0xffff0000, v207
	v_sub_f32_e32 v84, 1.0, v84
	v_sub_f32_e32 v85, 1.0, v85
	v_mul_f32_e32 v82, v82, v86
	v_mul_f32_e32 v83, v83, v87
	v_mul_f32_e32 v80, v84, v80
	v_mul_f32_e32 v81, v85, v81
	v_mul_f32_e32 v84, v76, v82
	v_mul_f32_e32 v85, v77, v83
	v_cvt_pk_bf16_f32 v82, v82, v83
	v_add_u32_e32 v83, 0x200, v220
	ds_write2_b32 v83, v2, v82 offset0:76 offset1:144
	v_cvt_pk_bf16_f32 v2, v84, v85
	v_add_u32_e32 v82, 0x2400, v221
	v_mul_f32_e32 v86, v78, v80
	v_mul_f32_e32 v87, v79, v81
	ds_write2_b32 v82, v88, v2 offset0:70 offset1:136
	v_cvt_pk_bf16_f32 v2, v80, v81
	ds_write2_b32 v89, v90, v2 offset0:140 offset1:208
	v_cvt_pk_bf16_f32 v2, v86, v87
	v_add_u32_e32 v80, 0x6800, v222
	ds_write2_b32 v80, v91, v2 offset0:48 offset1:128
	v_add_f32_e32 v80, v104, v106
	v_add_f32_e32 v81, v105, v107
	v_exp_f32_e32 v74, v74
	v_exp_f32_e32 v75, v75
	v_exp_f32_e32 v82, v80
	v_exp_f32_e32 v83, v81
	v_exp_f32_e64 v80, -v80
	v_exp_f32_e64 v81, -v81
	v_sub_f32_e32 v74, 1.0, v74
	v_sub_f32_e32 v75, 1.0, v75
	v_lshlrev_b32_e32 v84, 16, v209
	v_and_b32_e32 v85, 0xffff0000, v209
	v_mul_f32_e32 v82, v82, v84
	v_mul_f32_e32 v83, v83, v85
	v_mul_f32_e32 v74, v74, v80
	v_mul_f32_e32 v75, v75, v81
	v_add_f32_e32 v72, v72, v106
	v_add_f32_e32 v73, v73, v107
	v_mul_f32_e32 v80, v76, v82
	v_mul_f32_e32 v81, v77, v83
	v_mul_f32_e32 v84, v78, v74
	v_mul_f32_e32 v85, v79, v75
	v_cvt_pk_bf16_f32 v2, v82, v83
	v_cvt_pk_bf16_f32 v82, v74, v75
	v_exp_f32_e32 v74, v72
	v_exp_f32_e32 v68, v68
	v_exp_f32_e32 v69, v69
	v_exp_f32_e32 v75, v73
	v_exp_f32_e64 v72, -v72
	v_exp_f32_e64 v73, -v73
	v_cvt_pk_bf16_f32 v80, v80, v81
	ds_write_b32 v221, v80 offset:10024
	v_lshlrev_b32_e32 v80, 16, v225
	v_and_b32_e32 v81, 0xffff0000, v225
	v_sub_f32_e32 v68, 1.0, v68
	v_sub_f32_e32 v69, 1.0, v69
	v_mul_f32_e32 v74, v74, v80
	v_mul_f32_e32 v75, v75, v81
	v_mul_f32_e32 v68, v68, v72
	v_mul_f32_e32 v69, v69, v73
	v_mul_f32_e32 v72, v76, v74
	v_mul_f32_e32 v73, v77, v75
	v_cvt_pk_bf16_f32 v74, v74, v75
	v_add_u32_e32 v75, 0x400, v220
	ds_write2_b32 v75, v2, v74 offset0:84 offset1:152
	v_cvt_pk_bf16_f32 v2, v72, v73
	v_mul_f32_e32 v76, v78, v68
	v_mul_f32_e32 v77, v79, v69
	ds_write_b32 v221, v2 offset:10288
	v_cvt_pk_bf16_f32 v2, v68, v69
	v_add_u32_e32 v68, 0x4800, v220
	v_cvt_pk_bf16_f32 v83, v84, v85
	ds_write2_b32 v68, v82, v2 offset0:20 offset1:88
	v_cvt_pk_bf16_f32 v2, v76, v77
	v_add_u32_e32 v68, 0x6a00, v222
	ds_write2_b32 v68, v83, v2 offset0:80 offset1:160
	s_and_saveexec_b64 s[14:15], s[12:13]
	s_cbranch_execz .LBB0_1119
	v_exp_f32_e32 v68, v70
	v_exp_f32_e32 v69, v71
	ds_write_b64 v223, v[68:69] offset:46336

.LBB0_1181:
	v_lshl_add_u32 v84, s14, 13, v180
	s_andn2_b64 vcc, exec, s[42:43]
	v_lshl_add_u32 v85, s24, 1, v84
	s_cbranch_vccnz .LBB0_1183
	v_add_u32_e32 v86, s25, v85
	v_add_u32_e32 v87, s25, v86
	v_add_u32_e32 v88, s28, v87
	v_add_u32_e32 v89, s25, v88
	v_add_u32_e32 v90, s25, v89
	v_add_u32_e32 v91, s25, v90
	ds_read_u16 v99, v85
	ds_read_u16 v100, v84
	ds_read_u16 v101, v87
	ds_read_u16 v89, v89
	ds_read_u16 v90, v90
	ds_read_u16 v88, v88
	ds_read_u16 v102, v86
	v_add_u32_e32 v92, s28, v91
	ds_read_u16 v91, v91
	s_waitcnt lgkmcnt(7)
	v_lshlrev_b32_e32 v87, 16, v99
	s_waitcnt lgkmcnt(6)
	v_lshlrev_b32_e32 v86, 16, v100
	v_add_u32_e32 v93, s25, v92
	v_add_f32_e32 v68, v68, v86
	v_add_f32_e32 v69, v69, v87
	s_waitcnt lgkmcnt(1)
	v_lshlrev_b32_e32 v86, 16, v102
	v_lshlrev_b32_e32 v87, 16, v101
	v_add_u32_e32 v94, s25, v93
	v_add_f32_e32 v70, v70, v86
	v_add_f32_e32 v71, v71, v87
	v_lshlrev_b32_e32 v86, 16, v88
	v_lshlrev_b32_e32 v87, 16, v89
	ds_read_u16 v88, v92
	ds_read_u16 v89, v93
	v_add_u32_e32 v95, s25, v94
	v_add_f32_e32 v72, v72, v86
	v_add_f32_e32 v73, v73, v87
	v_lshlrev_b32_e32 v86, 16, v90
	s_waitcnt lgkmcnt(2)
	v_lshlrev_b32_e32 v87, 16, v91
	ds_read_u16 v90, v94
	ds_read_u16 v91, v95
	v_add_u32_e32 v96, s28, v95
	v_add_u32_e32 v97, s25, v96
	v_add_u32_e32 v98, s25, v97
	v_add_f32_e32 v74, v74, v86
	v_add_f32_e32 v75, v75, v87
	s_waitcnt lgkmcnt(3)
	v_lshlrev_b32_e32 v86, 16, v88
	s_waitcnt lgkmcnt(2)
	v_lshlrev_b32_e32 v87, 16, v89
	ds_read_u16 v88, v96
	ds_read_u16 v89, v97
	v_add_u32_e32 v103, s25, v98
	v_add_f32_e32 v76, v76, v86
	v_add_f32_e32 v77, v77, v87
	s_waitcnt lgkmcnt(3)
	v_lshlrev_b32_e32 v86, 16, v90
	s_waitcnt lgkmcnt(2)
	v_lshlrev_b32_e32 v87, 16, v91
	ds_read_u16 v90, v98
	ds_read_u16 v91, v103
	v_add_f32_e32 v78, v78, v86
	v_add_f32_e32 v79, v79, v87
	s_waitcnt lgkmcnt(3)
	v_lshlrev_b32_e32 v86, 16, v88
	s_waitcnt lgkmcnt(2)
	v_lshlrev_b32_e32 v87, 16, v89
	v_add_f32_e32 v80, v80, v86
	v_add_f32_e32 v81, v81, v87
	s_waitcnt lgkmcnt(1)
	v_lshlrev_b32_e32 v86, 16, v90
	s_waitcnt lgkmcnt(0)
	v_lshlrev_b32_e32 v87, 16, v91
	v_add_f32_e32 v82, v82, v86
	v_add_f32_e32 v83, v83, v87
.LBB0_1183:
	s_nop 6
	v_cvt_pk_bf16_f32 v68, v68, s0
	ds_write_b16 v84, v68
	v_cvt_pk_bf16_f32 v68, v69, s0
	ds_write_b16 v85, v68
	v_cvt_pk_bf16_f32 v68, v70, s0
	v_add_u32_e32 v69, s25, v85
	ds_write_b16 v69, v68
	v_cvt_pk_bf16_f32 v68, v71, s0
	v_add_u32_e32 v69, s25, v69
	ds_write_b16 v69, v68
	v_cvt_pk_bf16_f32 v68, v72, s0
	v_add_u32_e32 v69, s28, v69
	ds_write_b16 v69, v68
	v_cvt_pk_bf16_f32 v68, v73, s0
	v_add_u32_e32 v69, s25, v69
	ds_write_b16 v69, v68
	v_cvt_pk_bf16_f32 v68, v74, s0
	v_add_u32_e32 v69, s25, v69
	ds_write_b16 v69, v68
	v_cvt_pk_bf16_f32 v68, v75, s0
	v_add_u32_e32 v69, s25, v69
	ds_write_b16 v69, v68
	v_cvt_pk_bf16_f32 v68, v76, s0
	v_add_u32_e32 v69, s28, v69
	ds_write_b16 v69, v68
	v_cvt_pk_bf16_f32 v68, v77, s0
	v_add_u32_e32 v69, s25, v69
	ds_write_b16 v69, v68
	v_cvt_pk_bf16_f32 v68, v78, s0
	v_add_u32_e32 v69, s25, v69
	ds_write_b16 v69, v68
	v_cvt_pk_bf16_f32 v68, v79, s0
	v_add_u32_e32 v69, s25, v69
	ds_write_b16 v69, v68
	v_cvt_pk_bf16_f32 v68, v80, s0
	v_add_u32_e32 v69, s28, v69
	ds_write_b16 v69, v68
	v_cvt_pk_bf16_f32 v68, v81, s0
	v_add_u32_e32 v69, s25, v69
	ds_write_b16 v69, v68
	v_cvt_pk_bf16_f32 v68, v82, s0
	v_add_u32_e32 v69, s25, v69
	ds_write_b16 v69, v68
	v_cvt_pk_bf16_f32 v68, v83, s0
	v_add_u32_e32 v69, s25, v69
	ds_write_b16 v69, v68
	v_add_u32_e32 v201, s18, v179
	ds_read_b128 v[68:71], v201 offset:46432
	ds_read_b128 v[72:75], v201 offset:46400
	ds_read_b128 v[82:85], v201 offset:46368
	ds_read_b128 v[86:89], v201 offset:46336
	s_mov_b64 s[14:15], 0
	s_waitcnt lgkmcnt(3)
	v_mul_f32_e32 v80, v16, v68
	v_mul_f32_e32 v81, v17, v69
	s_waitcnt lgkmcnt(2)
	v_mul_f32_e32 v76, v12, v72
	v_mul_f32_e32 v77, v13, v73
	s_waitcnt lgkmcnt(1)
	v_mul_f32_e32 v72, v8, v82
	v_mul_f32_e32 v73, v9, v83
	v_mul_f32_e32 v82, v18, v70
	v_mul_f32_e32 v83, v19, v71
	v_mul_f32_e32 v78, v14, v74
	v_mul_f32_e32 v79, v15, v75
	v_mul_f32_e32 v74, v10, v84
	v_mul_f32_e32 v75, v11, v85
	s_waitcnt lgkmcnt(0)
	v_mul_f32_e32 v70, v6, v88
	v_mul_f32_e32 v71, v7, v89
	v_mul_f32_e32 v68, v4, v86
	v_mul_f32_e32 v69, v5, v87
	ds_read_b64_tr_b16 v[84:85], v188 offset:25856
	ds_read_b64_tr_b16 v[86:87], v188 offset:27136
	ds_read_b64_tr_b16 v[140:141], v189 offset:36096
	ds_read_b64_tr_b16 v[142:143], v189 offset:37376
	ds_read_b64_tr_b16 v[144:145], v189 offset:41216
	ds_read_b64_tr_b16 v[146:147], v189 offset:42496
	ds_read_b64_tr_b16 v[100:101], v188 offset:25920
	ds_read_b64_tr_b16 v[116:117], v188 offset:25984
	ds_read_b64_tr_b16 v[206:207], v188 offset:26048
	ds_read_b64_tr_b16 v[102:103], v188 offset:27200
	ds_read_b64_tr_b16 v[118:119], v188 offset:27264
	ds_read_b64_tr_b16 v[208:209], v188 offset:27328
	s_waitcnt lgkmcnt(8)
	v_mfma_f32_32x32x16_bf16 v[68:83], v[84:87], v[140:143], v[68:83]
	ds_read_b64_tr_b16 v[84:85], v188 offset:30976
	ds_read_b64_tr_b16 v[86:87], v188 offset:32256
	ds_read_b128 v[104:107], v201 offset:46464
	ds_read_b128 v[88:91], v201 offset:46496
	ds_read_b128 v[92:95], v201 offset:46528
	ds_read_b128 v[96:99], v201 offset:46560
	ds_read_b64_tr_b16 v[108:109], v188 offset:31040
	ds_read_b64_tr_b16 v[120:121], v188 offset:31104
	ds_read_b64_tr_b16 v[210:211], v188 offset:31168
	ds_read_b64_tr_b16 v[110:111], v188 offset:32320
	ds_read_b64_tr_b16 v[122:123], v188 offset:32384
	ds_read_b64_tr_b16 v[212:213], v188 offset:32448
	s_waitcnt lgkmcnt(6)
	v_mul_f32_e32 v96, v64, v96
	v_mul_f32_e32 v97, v65, v97
	v_mul_f32_e32 v92, v60, v92
	v_mul_f32_e32 v93, v61, v93
	v_mul_f32_e32 v88, v56, v88
	v_mul_f32_e32 v89, v57, v89
	v_mul_f32_e32 v98, v66, v98
	v_mul_f32_e32 v99, v67, v99
	v_mul_f32_e32 v94, v62, v94
	v_mul_f32_e32 v95, v63, v95
	v_mul_f32_e32 v90, v58, v90
	v_mul_f32_e32 v91, v59, v91
	v_mfma_f32_32x32x16_bf16 v[68:83], v[84:87], v[144:147], v[68:83]
	v_mul_f32_e64 v86, v54, v106
	v_mul_f32_e64 v87, v55, v107
	v_mul_f32_e64 v84, v52, v104
	v_mul_f32_e64 v85, v53, v105
	s_nop 1
	v_mfma_f32_32x32x16_bf16 v[84:99], v[100:103], v[140:143], v[84:99]
	ds_read_b128 v[100:103], v201 offset:46688
	ds_read_b128 v[104:107], v201 offset:46656
	ds_read_b128 v[124:127], v201 offset:46624
	ds_read_b128 v[128:131], v201 offset:46592
	s_waitcnt lgkmcnt(3)
	v_mul_f32_e32 v112, v48, v100
	v_mul_f32_e32 v113, v49, v101
	v_mul_f32_e32 v114, v50, v102
	v_mul_f32_e32 v115, v51, v103
	s_waitcnt lgkmcnt(0)
	v_mul_f32_e32 v102, v38, v130
	v_mul_f32_e32 v103, v39, v131
	v_mul_f32_e32 v100, v36, v128
	v_mul_f32_e32 v101, v37, v129
	v_mfma_f32_32x32x16_bf16 v[84:99], v[108:111], v[144:147], v[84:99]
	v_mul_f32_e64 v108, v44, v104
	v_mul_f32_e64 v109, v45, v105
	v_mul_f32_e64 v104, v40, v124
	v_mul_f32_e64 v105, v41, v125
	v_mul_f32_e64 v110, v46, v106
	v_mul_f32_e64 v111, v47, v107
	v_mul_f32_e32 v106, v42, v126
	v_mul_f32_e32 v107, v43, v127
	s_nop 1
	v_mfma_f32_32x32x16_bf16 v[100:115], v[116:119], v[140:143], v[100:115]
	ds_read_b128 v[116:119], v201 offset:46816
	ds_read_b128 v[124:127], v201 offset:46784
	ds_read_b128 v[214:217], v201 offset:46752
	ds_read_b128 v[218:221], v201 offset:46720
	s_waitcnt lgkmcnt(3)
	v_mul_f32_e32 v128, v32, v116
	v_mul_f32_e32 v129, v33, v117
	s_waitcnt lgkmcnt(2)
	v_mul_f32_e32 v124, v28, v124
	v_mul_f32_e32 v125, v29, v125
	v_mul_f32_e32 v130, v34, v118
	v_mul_f32_e32 v131, v35, v119
	v_mul_f32_e32 v126, v30, v126
	v_mul_f32_e32 v127, v31, v127
	s_waitcnt lgkmcnt(0)
	v_mul_f32_e32 v118, v22, v220
	v_mul_f32_e32 v119, v23, v221
	v_mfma_f32_32x32x16_bf16 v[100:115], v[120:123], v[144:147], v[100:115]
	v_mul_f32_e64 v120, v24, v214
	v_mul_f32_e64 v121, v25, v215
	v_mul_f32_e64 v122, v26, v216
	v_mul_f32_e64 v123, v27, v217
	v_mul_f32_e64 v116, v20, v218
	v_mul_f32_e64 v117, v21, v219
	s_nop 1
	v_mfma_f32_32x32x16_bf16 v[116:131], v[206:209], v[140:143], v[116:131]
	v_mfma_f32_32x32x16_bf16 v[116:131], v[210:213], v[144:147], v[116:131]
.LBB0_1184:
	s_and_b64 vcc, exec, s[14:15]
	s_cbranch_vccz .LBB0_1176
	s_waitcnt vmcnt(0)
	v_cvt_f32_f16_sdwa v81, v170 dst_sel:DWORD dst_unused:UNUSED_PAD src0_sel:WORD_1
	v_cvt_f32_f16_e32 v80, v170
	v_cvt_f32_f16_sdwa v83, v172 dst_sel:DWORD dst_unused:UNUSED_PAD src0_sel:WORD_1
	v_cvt_f32_f16_e32 v82, v172
	v_cvt_f32_f16_sdwa v85, v174 dst_sel:DWORD dst_unused:UNUSED_PAD src0_sel:WORD_1
	v_cvt_f32_f16_e32 v84, v174
	v_cvt_f32_f16_sdwa v87, v176 dst_sel:DWORD dst_unused:UNUSED_PAD src0_sel:WORD_1
	v_cvt_f32_f16_e32 v86, v176
	v_add_f32_e32 v88, 0, v80
	v_add_f32_e32 v89, 0, v81
	v_cvt_f32_f16_sdwa v97, v178 dst_sel:DWORD dst_unused:UNUSED_PAD src0_sel:WORD_1
	v_cvt_f32_f16_e32 v96, v178
	v_add_f32_e32 v90, v88, v82
	v_add_f32_e32 v91, v89, v83
	v_cvt_f32_f16_sdwa v99, v182 dst_sel:DWORD dst_unused:UNUSED_PAD src0_sel:WORD_1
	v_cvt_f32_f16_e32 v98, v182
	v_add_f32_e32 v92, v90, v84
	v_add_f32_e32 v93, v91, v85
	v_cvt_f32_f16_sdwa v75, v184 dst_sel:DWORD dst_unused:UNUSED_PAD src0_sel:WORD_1
	v_cvt_f32_f16_e32 v74, v184
	v_add_f32_e32 v94, v92, v86
	v_add_f32_e32 v95, v93, v87
	v_cvt_f32_f16_sdwa v69, v199 dst_sel:DWORD dst_unused:UNUSED_PAD src0_sel:WORD_1
	v_cvt_f32_f16_e32 v68, v199
	v_add_f32_e32 v100, v94, v96
	v_add_f32_e32 v101, v95, v97
	v_exp_f32_e32 v80, v80
	v_add_f32_e32 v102, v100, v98
	v_add_f32_e32 v103, v101, v99
	v_exp_f32_e32 v81, v81
	v_add_f32_e32 v104, v102, v74
	v_add_f32_e32 v105, v103, v75
	ds_write_b128 v190, v[136:139] offset:36096
	ds_write_b128 v190, v[132:135] offset:36112
	v_add_f32_e32 v72, v104, v68
	v_add_f32_e32 v73, v105, v69
	ds_bpermute_b32 v70, v200, v72
	ds_bpermute_b32 v71, v200, v73
	ds_bpermute_b32 v76, v200, v72 offset:64
	ds_bpermute_b32 v77, v200, v73 offset:64
	ds_bpermute_b32 v78, v200, v72 offset:128
	ds_bpermute_b32 v79, v200, v73 offset:128
	ds_bpermute_b32 v106, v200, v72 offset:192
	ds_bpermute_b32 v107, v200, v73 offset:192
	s_waitcnt lgkmcnt(6)
	v_cndmask_b32_e64 v109, 0, v71, s[6:7]
	v_cndmask_b32_e64 v108, 0, v70, s[6:7]
	s_waitcnt lgkmcnt(4)
	v_cndmask_b32_e64 v111, 0, v77, s[8:9]
	v_cndmask_b32_e64 v110, 0, v76, s[8:9]
	v_add_f32_e32 v108, v108, v110
	v_add_f32_e32 v109, v109, v111
	s_waitcnt lgkmcnt(2)
	v_cndmask_b32_e64 v111, 0, v79, s[10:11]
	v_cndmask_b32_e64 v110, 0, v78, s[10:11]
	v_add_f32_e32 v108, v108, v110
	v_add_f32_e32 v109, v109, v111
	v_add_f32_e32 v110, v70, v76
	v_add_f32_e32 v111, v71, v77
	v_sub_f32_e32 v80, 1.0, v80
	v_sub_f32_e32 v81, 1.0, v81
	v_add_f32_e32 v70, v110, v78
	v_add_f32_e32 v71, v111, v79
	v_exp_f32_e32 v76, v110
	s_waitcnt lgkmcnt(0)
	v_add_f32_e32 v70, v70, v106
	v_add_f32_e32 v71, v71, v107
	v_sub_f32_e32 v106, v108, v110
	v_sub_f32_e32 v107, v109, v111
	v_exp_f32_e32 v77, v111
	v_add_f32_e32 v88, v88, v106
	v_add_f32_e32 v89, v89, v107
	v_sub_f32_e32 v78, v70, v110
	v_sub_f32_e32 v79, v71, v111
	v_exp_f32_e32 v108, v88
	v_exp_f32_e32 v109, v89
	v_exp_f32_e64 v88, -v88
	v_exp_f32_e64 v89, -v89
	v_exp_f32_e32 v78, v78
	v_exp_f32_e32 v79, v79
	v_lshlrev_b32_e32 v110, 16, v169
	v_and_b32_e32 v111, 0xffff0000, v169
	v_mul_f32_e32 v108, v108, v110
	v_mul_f32_e32 v109, v109, v111
	v_mul_f32_e32 v80, v80, v88
	v_mul_f32_e32 v81, v81, v89
	v_mul_f32_e32 v88, v76, v108
	v_mul_f32_e32 v89, v77, v109
	v_mul_f32_e32 v110, v78, v80
	v_mul_f32_e32 v111, v79, v81
	v_cvt_pk_bf16_f32 v108, v108, v109
	v_cvt_pk_bf16_f32 v88, v88, v89
	v_cvt_pk_bf16_f32 v80, v80, v81
	ds_write_b32 v191, v108
	ds_write_b32 v192, v88 offset:8704
	ds_write_b32 v191, v80 offset:17152
	v_cvt_pk_bf16_f32 v80, v110, v111
	ds_write_b32 v193, v80 offset:25856
	v_add_f32_e32 v80, v90, v106
	v_add_f32_e32 v81, v91, v107
	v_exp_f32_e32 v82, v82
	v_exp_f32_e32 v83, v83
	v_exp_f32_e32 v88, v80
	v_exp_f32_e32 v89, v81
	v_exp_f32_e64 v80, -v80
	v_exp_f32_e64 v81, -v81
	v_sub_f32_e32 v82, 1.0, v82
	v_sub_f32_e32 v83, 1.0, v83
	v_lshlrev_b32_e32 v90, 16, v171
	v_and_b32_e32 v91, 0xffff0000, v171
	v_mul_f32_e32 v88, v88, v90
	v_mul_f32_e32 v89, v89, v91
	v_mul_f32_e32 v80, v82, v80
	v_mul_f32_e32 v81, v83, v81
	v_mul_f32_e32 v82, v76, v88
	v_mul_f32_e32 v83, v77, v89
	v_mul_f32_e32 v90, v78, v80
	v_mul_f32_e32 v91, v79, v81
	v_cvt_pk_bf16_f32 v88, v88, v89
	v_cvt_pk_bf16_f32 v80, v80, v81
	v_cvt_pk_bf16_f32 v82, v82, v83
	ds_write2st64_b32 v195, v88, v80 offset1:67
	v_cvt_pk_bf16_f32 v80, v90, v91
	ds_write_b32 v196, v82 offset:8704
	ds_write_b32 v197, v80 offset:25856
	v_add_f32_e32 v80, v92, v106
	v_add_f32_e32 v81, v93, v107
	v_exp_f32_e32 v84, v84
	v_exp_f32_e32 v82, v80
	v_exp_f32_e32 v85, v85
	v_exp_f32_e32 v83, v81
	v_exp_f32_e64 v80, -v80
	v_exp_f32_e64 v81, -v81
	v_lshlrev_b32_e32 v88, 16, v173
	v_and_b32_e32 v89, 0xffff0000, v173
	v_sub_f32_e32 v84, 1.0, v84
	v_sub_f32_e32 v85, 1.0, v85
	v_mul_f32_e32 v82, v82, v88
	v_mul_f32_e32 v83, v83, v89
	v_mul_f32_e32 v80, v84, v80
	v_mul_f32_e32 v81, v85, v81
	v_mul_f32_e32 v84, v76, v82
	v_mul_f32_e32 v85, v77, v83
	v_mul_f32_e32 v88, v78, v80
	v_mul_f32_e32 v89, v79, v81
	v_cvt_pk_bf16_f32 v91, v84, v85
	v_cvt_pk_bf16_f32 v92, v80, v81
	v_add_f32_e32 v80, v94, v106
	v_add_f32_e32 v81, v95, v107
	v_exp_f32_e32 v84, v86
	v_exp_f32_e32 v85, v87
	v_cvt_pk_bf16_f32 v90, v82, v83
	v_exp_f32_e32 v82, v80
	v_exp_f32_e32 v83, v81
	v_exp_f32_e64 v80, -v80
	v_exp_f32_e64 v81, -v81
	v_sub_f32_e32 v84, 1.0, v84
	v_sub_f32_e32 v85, 1.0, v85
	v_lshlrev_b32_e32 v86, 16, v175
	v_and_b32_e32 v87, 0xffff0000, v175
	v_mul_f32_e32 v82, v82, v86
	v_mul_f32_e32 v83, v83, v87
	v_mul_f32_e32 v80, v84, v80
	v_mul_f32_e32 v81, v85, v81
	v_cvt_pk_bf16_f32 v88, v88, v89
	v_mul_f32_e32 v84, v76, v82
	v_mul_f32_e32 v85, v77, v83
	v_mul_f32_e32 v86, v78, v80
	v_mul_f32_e32 v87, v79, v81
	v_cvt_pk_bf16_f32 v82, v82, v83
	v_cvt_pk_bf16_f32 v80, v80, v81
	v_add_u32_e32 v89, 0x4400, v195
	ds_write2_b32 v195, v90, v82 offset0:68 offset1:136
	v_cvt_pk_bf16_f32 v82, v84, v85
	v_add_u32_e32 v83, 0x2200, v196
	ds_write2_b32 v89, v92, v80 offset0:4 offset1:72
	v_cvt_pk_bf16_f32 v80, v86, v87
	v_add_u32_e32 v81, 0x6400, v197
	ds_write2_b32 v83, v91, v82 offset0:66 offset1:132
	ds_write2_b32 v81, v88, v80 offset0:144 offset1:224
	v_add_f32_e32 v80, v100, v106
	v_add_f32_e32 v81, v101, v107
	v_exp_f32_e32 v84, v96
	v_exp_f32_e32 v82, v80
	v_exp_f32_e32 v85, v97
	v_exp_f32_e32 v83, v81
	v_exp_f32_e64 v80, -v80
	v_exp_f32_e64 v81, -v81
	v_lshlrev_b32_e32 v86, 16, v177
	v_and_b32_e32 v87, 0xffff0000, v177
	v_sub_f32_e32 v84, 1.0, v84
	v_sub_f32_e32 v85, 1.0, v85
	v_mul_f32_e32 v82, v82, v86
	v_mul_f32_e32 v83, v83, v87
	v_mul_f32_e32 v80, v84, v80
	v_mul_f32_e32 v81, v85, v81
	v_mul_f32_e32 v84, v76, v82
	v_mul_f32_e32 v85, v77, v83
	v_mul_f32_e32 v86, v78, v80
	v_mul_f32_e32 v87, v79, v81
	v_cvt_pk_bf16_f32 v90, v84, v85
	v_cvt_pk_bf16_f32 v91, v80, v81
	v_add_f32_e32 v80, v102, v106
	v_add_f32_e32 v81, v103, v107
	v_exp_f32_e32 v84, v98
	v_exp_f32_e32 v85, v99
	v_cvt_pk_bf16_f32 v88, v82, v83
	v_exp_f32_e32 v82, v80
	v_exp_f32_e32 v83, v81
	v_exp_f32_e64 v80, -v80
	v_exp_f32_e64 v81, -v81
	v_cvt_pk_bf16_f32 v92, v86, v87
	v_sub_f32_e32 v84, 1.0, v84
	v_sub_f32_e32 v85, 1.0, v85
	v_lshlrev_b32_e32 v86, 16, v181
	v_and_b32_e32 v87, 0xffff0000, v181
	v_mul_f32_e32 v82, v82, v86
	v_mul_f32_e32 v83, v83, v87
	v_mul_f32_e32 v80, v84, v80
	v_mul_f32_e32 v81, v85, v81
	v_mul_f32_e32 v84, v76, v82
	v_mul_f32_e32 v85, v77, v83
	v_mul_f32_e32 v86, v78, v80
	v_mul_f32_e32 v87, v79, v81
	v_cvt_pk_bf16_f32 v82, v82, v83
	v_add_u32_e32 v83, 0x200, v195
	v_cvt_pk_bf16_f32 v80, v80, v81
	ds_write2_b32 v83, v88, v82 offset0:76 offset1:144
	v_cvt_pk_bf16_f32 v82, v84, v85
	v_add_u32_e32 v83, 0x2400, v196
	ds_write2_b32 v89, v91, v80 offset0:140 offset1:208
	v_cvt_pk_bf16_f32 v80, v86, v87
	v_add_u32_e32 v81, 0x6800, v197
	ds_write2_b32 v83, v90, v82 offset0:70 offset1:136
	ds_write2_b32 v81, v92, v80 offset0:48 offset1:128
	v_add_f32_e32 v80, v104, v106
	v_add_f32_e32 v81, v105, v107
	v_exp_f32_e32 v74, v74
	v_exp_f32_e32 v75, v75
	v_exp_f32_e32 v82, v80
	v_exp_f32_e32 v83, v81
	v_exp_f32_e64 v80, -v80
	v_exp_f32_e64 v81, -v81
	v_sub_f32_e32 v74, 1.0, v74
	v_sub_f32_e32 v75, 1.0, v75
	v_lshlrev_b32_e32 v84, 16, v183
	v_and_b32_e32 v85, 0xffff0000, v183
	v_mul_f32_e32 v82, v82, v84
	v_mul_f32_e32 v83, v83, v85
	v_mul_f32_e32 v74, v74, v80
	v_mul_f32_e32 v75, v75, v81
	v_add_f32_e32 v72, v72, v106
	v_add_f32_e32 v73, v73, v107
	v_exp_f32_e32 v68, v68
	v_exp_f32_e32 v69, v69
	v_mul_f32_e32 v80, v76, v82
	v_mul_f32_e32 v81, v77, v83
	v_mul_f32_e32 v84, v78, v74
	v_mul_f32_e32 v85, v79, v75
	v_cvt_pk_bf16_f32 v82, v82, v83
	v_cvt_pk_bf16_f32 v83, v74, v75
	v_exp_f32_e32 v74, v72
	v_exp_f32_e32 v75, v73
	v_exp_f32_e64 v72, -v72
	v_exp_f32_e64 v73, -v73
	v_cvt_pk_bf16_f32 v80, v80, v81
	ds_write_b32 v196, v80 offset:10024
	v_sub_f32_e32 v68, 1.0, v68
	v_sub_f32_e32 v69, 1.0, v69
	v_lshlrev_b32_e32 v80, 16, v194
	v_and_b32_e32 v81, 0xffff0000, v194
	v_mul_f32_e32 v74, v74, v80
	v_mul_f32_e32 v75, v75, v81
	v_mul_f32_e32 v68, v68, v72
	v_mul_f32_e32 v69, v69, v73
	v_mul_f32_e32 v72, v76, v74
	v_mul_f32_e32 v73, v77, v75
	v_mul_f32_e32 v76, v78, v68
	v_mul_f32_e32 v77, v79, v69
	v_cvt_pk_bf16_f32 v68, v68, v69
	v_add_u32_e32 v69, 0x4800, v195
	v_cvt_pk_bf16_f32 v84, v84, v85
	v_cvt_pk_bf16_f32 v74, v74, v75
	v_add_u32_e32 v75, 0x400, v195
	v_cvt_pk_bf16_f32 v72, v72, v73
	ds_write2_b32 v69, v83, v68 offset0:20 offset1:88
	v_cvt_pk_bf16_f32 v68, v76, v77
	v_add_u32_e32 v69, 0x6a00, v197
	ds_write2_b32 v75, v82, v74 offset0:84 offset1:152
	ds_write_b32 v196, v72 offset:10288
	ds_write2_b32 v69, v84, v68 offset0:80 offset1:160
	s_and_saveexec_b64 s[14:15], s[12:13]
	s_cbranch_execz .LBB0_1187
	v_exp_f32_e32 v68, v70
	v_exp_f32_e32 v69, v71
	ds_write_b64 v198, v[68:69] offset:46336

.LBB0_1338:
	v_lshl_add_u32 v82, s14, 13, v199
	s_andn2_b64 vcc, exec, s[38:39]
	v_lshl_add_u32 v83, s16, 1, v82
	s_cbranch_vccnz .LBB0_1340
	v_add_u32_e32 v84, s17, v83
	v_add_u32_e32 v85, s17, v84
	v_add_u32_e32 v86, s18, v85
	v_add_u32_e32 v87, s17, v86
	v_add_u32_e32 v88, s17, v87
	v_add_u32_e32 v89, s17, v88
	ds_read_u16 v97, v83
	ds_read_u16 v98, v82
	ds_read_u16 v99, v85
	ds_read_u16 v87, v87
	ds_read_u16 v88, v88
	ds_read_u16 v86, v86
	ds_read_u16 v100, v84
	v_add_u32_e32 v90, s18, v89
	ds_read_u16 v89, v89
	s_waitcnt lgkmcnt(7)
	v_lshlrev_b32_e32 v85, 16, v97
	s_waitcnt lgkmcnt(6)
	v_lshlrev_b32_e32 v84, 16, v98
	v_add_u32_e32 v91, s17, v90
	v_add_f32_e32 v66, v66, v84
	v_add_f32_e32 v67, v67, v85
	s_waitcnt lgkmcnt(1)
	v_lshlrev_b32_e32 v84, 16, v100
	v_lshlrev_b32_e32 v85, 16, v99
	v_add_u32_e32 v92, s17, v91
	v_add_f32_e32 v68, v68, v84
	v_add_f32_e32 v69, v69, v85
	v_lshlrev_b32_e32 v84, 16, v86
	v_lshlrev_b32_e32 v85, 16, v87
	ds_read_u16 v86, v90
	ds_read_u16 v87, v91
	v_add_u32_e32 v93, s17, v92
	v_add_f32_e32 v70, v70, v84
	v_add_f32_e32 v71, v71, v85
	v_lshlrev_b32_e32 v84, 16, v88
	s_waitcnt lgkmcnt(2)
	v_lshlrev_b32_e32 v85, 16, v89
	ds_read_u16 v88, v92
	ds_read_u16 v89, v93
	v_add_u32_e32 v94, s18, v93
	v_add_u32_e32 v95, s17, v94
	v_add_u32_e32 v96, s17, v95
	v_add_f32_e32 v72, v72, v84
	v_add_f32_e32 v73, v73, v85
	s_waitcnt lgkmcnt(3)
	v_lshlrev_b32_e32 v84, 16, v86
	s_waitcnt lgkmcnt(2)
	v_lshlrev_b32_e32 v85, 16, v87
	ds_read_u16 v86, v94
	ds_read_u16 v87, v95
	v_add_u32_e32 v101, s17, v96
	v_add_f32_e32 v74, v74, v84
	v_add_f32_e32 v75, v75, v85
	s_waitcnt lgkmcnt(3)
	v_lshlrev_b32_e32 v84, 16, v88
	s_waitcnt lgkmcnt(2)
	v_lshlrev_b32_e32 v85, 16, v89
	ds_read_u16 v88, v96
	ds_read_u16 v89, v101
	v_add_f32_e32 v76, v76, v84
	v_add_f32_e32 v77, v77, v85
	s_waitcnt lgkmcnt(3)
	v_lshlrev_b32_e32 v84, 16, v86
	s_waitcnt lgkmcnt(2)
	v_lshlrev_b32_e32 v85, 16, v87
	v_add_f32_e32 v78, v78, v84
	v_add_f32_e32 v79, v79, v85
	s_waitcnt lgkmcnt(1)
	v_lshlrev_b32_e32 v84, 16, v88
	s_waitcnt lgkmcnt(0)
	v_lshlrev_b32_e32 v85, 16, v89
	v_add_f32_e32 v80, v80, v84
	v_add_f32_e32 v81, v81, v85
.LBB0_1340:
	s_nop 6
	v_cvt_pk_bf16_f32 v66, v66, s0
	ds_write_b16 v82, v66
	v_cvt_pk_bf16_f32 v66, v67, s0
	ds_write_b16 v83, v66
	v_cvt_pk_bf16_f32 v66, v68, s0
	v_add_u32_e32 v67, s17, v83
	ds_write_b16 v67, v66
	v_cvt_pk_bf16_f32 v66, v69, s0
	v_add_u32_e32 v67, s17, v67
	ds_write_b16 v67, v66
	v_cvt_pk_bf16_f32 v66, v70, s0
	v_add_u32_e32 v67, s18, v67
	ds_write_b16 v67, v66
	v_cvt_pk_bf16_f32 v66, v71, s0
	v_add_u32_e32 v67, s17, v67
	ds_write_b16 v67, v66
	v_cvt_pk_bf16_f32 v66, v72, s0
	v_add_u32_e32 v67, s17, v67
	ds_write_b16 v67, v66
	v_cvt_pk_bf16_f32 v66, v73, s0
	v_add_u32_e32 v67, s17, v67
	ds_write_b16 v67, v66
	v_cvt_pk_bf16_f32 v66, v74, s0
	v_add_u32_e32 v67, s18, v67
	ds_write_b16 v67, v66
	v_cvt_pk_bf16_f32 v66, v75, s0
	v_add_u32_e32 v67, s17, v67
	ds_write_b16 v67, v66
	v_cvt_pk_bf16_f32 v66, v76, s0
	v_add_u32_e32 v67, s17, v67
	ds_write_b16 v67, v66
	v_cvt_pk_bf16_f32 v66, v77, s0
	v_add_u32_e32 v67, s17, v67
	ds_write_b16 v67, v66
	v_cvt_pk_bf16_f32 v66, v78, s0
	v_add_u32_e32 v67, s18, v67
	ds_write_b16 v67, v66
	v_cvt_pk_bf16_f32 v66, v79, s0
	v_add_u32_e32 v67, s17, v67
	ds_write_b16 v67, v66
	v_cvt_pk_bf16_f32 v66, v80, s0
	v_add_u32_e32 v67, s17, v67
	ds_write_b16 v67, v66
	v_cvt_pk_bf16_f32 v66, v81, s0
	v_add_u32_e32 v67, s17, v67
	ds_write_b16 v67, v66
	v_add_u32_e32 v217, s2, v196
	ds_read_b128 v[66:69], v217 offset:46432
	ds_read_b128 v[70:73], v217 offset:46400
	ds_read_b128 v[80:83], v217 offset:46368
	ds_read_b128 v[84:87], v217 offset:46336
	s_mov_b64 s[14:15], 0
	s_waitcnt lgkmcnt(3)
	v_mul_f32_e32 v78, v14, v66
	v_mul_f32_e32 v79, v15, v67
	s_waitcnt lgkmcnt(2)
	v_mul_f32_e32 v74, v10, v70
	v_mul_f32_e32 v75, v11, v71
	s_waitcnt lgkmcnt(1)
	v_mul_f32_e32 v70, v6, v80
	v_mul_f32_e32 v71, v7, v81
	v_mul_f32_e32 v80, v16, v68
	v_mul_f32_e32 v81, v17, v69
	v_mul_f32_e32 v76, v12, v72
	v_mul_f32_e32 v77, v13, v73
	v_mul_f32_e32 v72, v8, v82
	v_mul_f32_e32 v73, v9, v83
	s_waitcnt lgkmcnt(0)
	v_mul_f32_e32 v68, v4, v86
	v_mul_f32_e32 v69, v5, v87
	v_mul_f32_e32 v66, v2, v84
	v_mul_f32_e32 v67, v3, v85
	ds_read_b64_tr_b16 v[82:83], v205 offset:25856
	ds_read_b64_tr_b16 v[84:85], v205 offset:27136
	ds_read_b64_tr_b16 v[138:139], v206 offset:36096
	ds_read_b64_tr_b16 v[140:141], v206 offset:37376
	ds_read_b64_tr_b16 v[142:143], v206 offset:41216
	ds_read_b64_tr_b16 v[144:145], v206 offset:42496
	ds_read_b64_tr_b16 v[98:99], v205 offset:25920
	ds_read_b64_tr_b16 v[114:115], v205 offset:25984
	ds_read_b64_tr_b16 v[218:219], v205 offset:26048
	ds_read_b64_tr_b16 v[100:101], v205 offset:27200
	ds_read_b64_tr_b16 v[116:117], v205 offset:27264
	ds_read_b64_tr_b16 v[220:221], v205 offset:27328
	s_waitcnt lgkmcnt(8)
	v_mfma_f32_32x32x16_bf16 v[66:81], v[82:85], v[138:141], v[66:81]
	ds_read_b64_tr_b16 v[82:83], v205 offset:30976
	ds_read_b64_tr_b16 v[84:85], v205 offset:32256
	ds_read_b128 v[102:105], v217 offset:46464
	ds_read_b128 v[86:89], v217 offset:46496
	ds_read_b128 v[90:93], v217 offset:46528
	ds_read_b128 v[94:97], v217 offset:46560
	ds_read_b64_tr_b16 v[106:107], v205 offset:31040
	ds_read_b64_tr_b16 v[118:119], v205 offset:31104
	ds_read_b64_tr_b16 v[222:223], v205 offset:31168
	ds_read_b64_tr_b16 v[108:109], v205 offset:32320
	ds_read_b64_tr_b16 v[120:121], v205 offset:32384
	ds_read_b64_tr_b16 v[224:225], v205 offset:32448
	s_waitcnt lgkmcnt(6)
	v_mul_f32_e32 v94, v30, v94
	v_mul_f32_e32 v95, v31, v95
	v_mul_f32_e32 v90, v26, v90
	v_mul_f32_e32 v91, v27, v91
	v_mul_f32_e32 v86, v22, v86
	v_mul_f32_e32 v87, v23, v87
	v_mul_f32_e32 v96, v32, v96
	v_mul_f32_e32 v97, v33, v97
	v_mul_f32_e32 v92, v28, v92
	v_mul_f32_e32 v93, v29, v93
	v_mul_f32_e32 v88, v24, v88
	v_mul_f32_e32 v89, v25, v89
	v_mfma_f32_32x32x16_bf16 v[66:81], v[82:85], v[142:145], v[66:81]
	v_mul_f32_e64 v84, v20, v104
	v_mul_f32_e64 v85, v21, v105
	v_mul_f32_e64 v82, v18, v102
	v_mul_f32_e64 v83, v19, v103
	s_nop 1
	v_mfma_f32_32x32x16_bf16 v[82:97], v[98:101], v[138:141], v[82:97]
	ds_read_b128 v[98:101], v217 offset:46688
	ds_read_b128 v[102:105], v217 offset:46656
	ds_read_b128 v[122:125], v217 offset:46624
	ds_read_b128 v[126:129], v217 offset:46592
	s_waitcnt lgkmcnt(3)
	v_mul_f32_e32 v110, v46, v98
	v_mul_f32_e32 v111, v47, v99
	v_mul_f32_e32 v112, v48, v100
	v_mul_f32_e32 v113, v49, v101
	s_waitcnt lgkmcnt(0)
	v_mul_f32_e32 v100, v36, v128
	v_mul_f32_e32 v101, v37, v129
	v_mul_f32_e32 v98, v34, v126
	v_mul_f32_e32 v99, v35, v127
	v_mfma_f32_32x32x16_bf16 v[82:97], v[106:109], v[142:145], v[82:97]
	v_mul_f32_e64 v106, v42, v102
	v_mul_f32_e64 v107, v43, v103
	v_mul_f32_e64 v102, v38, v122
	v_mul_f32_e64 v103, v39, v123
	v_mul_f32_e64 v108, v44, v104
	v_mul_f32_e64 v109, v45, v105
	v_mul_f32_e32 v104, v40, v124
	v_mul_f32_e32 v105, v41, v125
	s_nop 1
	v_mfma_f32_32x32x16_bf16 v[98:113], v[114:117], v[138:141], v[98:113]
	ds_read_b128 v[114:117], v217 offset:46816
	ds_read_b128 v[122:125], v217 offset:46784
	ds_read_b128 v[226:229], v217 offset:46752
	ds_read_b128 v[230:233], v217 offset:46720
	s_waitcnt lgkmcnt(3)
	v_mul_f32_e32 v126, v62, v114
	v_mul_f32_e32 v127, v63, v115
	s_waitcnt lgkmcnt(2)
	v_mul_f32_e32 v122, v58, v122
	v_mul_f32_e32 v123, v59, v123
	v_mul_f32_e32 v128, v64, v116
	v_mul_f32_e32 v129, v65, v117
	v_mul_f32_e32 v124, v60, v124
	v_mul_f32_e32 v125, v61, v125
	s_waitcnt lgkmcnt(0)
	v_mul_f32_e32 v116, v52, v232
	v_mul_f32_e32 v117, v53, v233
	v_mfma_f32_32x32x16_bf16 v[98:113], v[118:121], v[142:145], v[98:113]
	v_mul_f32_e64 v118, v54, v226
	v_mul_f32_e64 v119, v55, v227
	v_mul_f32_e64 v120, v56, v228
	v_mul_f32_e64 v121, v57, v229
	v_mul_f32_e64 v114, v50, v230
	v_mul_f32_e64 v115, v51, v231
	s_nop 1
	v_mfma_f32_32x32x16_bf16 v[114:129], v[218:221], v[138:141], v[114:129]
	v_mfma_f32_32x32x16_bf16 v[114:129], v[222:225], v[142:145], v[114:129]
.LBB0_1341:
	s_and_b64 vcc, exec, s[14:15]
	s_cbranch_vccz .LBB0_1333
	s_waitcnt vmcnt(16)
	v_cvt_f32_f16_sdwa v79, v184 dst_sel:DWORD dst_unused:UNUSED_PAD src0_sel:WORD_1
	v_cvt_f32_f16_e32 v78, v184
	s_waitcnt vmcnt(14)
	v_cvt_f32_f16_sdwa v81, v186 dst_sel:DWORD dst_unused:UNUSED_PAD src0_sel:WORD_1
	v_cvt_f32_f16_e32 v80, v186
	s_waitcnt vmcnt(12)
	v_cvt_f32_f16_sdwa v83, v188 dst_sel:DWORD dst_unused:UNUSED_PAD src0_sel:WORD_1
	v_cvt_f32_f16_e32 v82, v188
	s_waitcnt vmcnt(10)
	v_cvt_f32_f16_sdwa v85, v190 dst_sel:DWORD dst_unused:UNUSED_PAD src0_sel:WORD_1
	v_cvt_f32_f16_e32 v84, v190
	v_add_f32_e32 v86, 0, v78
	v_add_f32_e32 v87, 0, v79
	s_waitcnt vmcnt(8)
	v_cvt_f32_f16_sdwa v95, v193 dst_sel:DWORD dst_unused:UNUSED_PAD src0_sel:WORD_1
	v_cvt_f32_f16_e32 v94, v193
	v_add_f32_e32 v88, v86, v80
	v_add_f32_e32 v89, v87, v81
	s_waitcnt vmcnt(6)
	v_cvt_f32_f16_sdwa v97, v198 dst_sel:DWORD dst_unused:UNUSED_PAD src0_sel:WORD_1
	v_cvt_f32_f16_e32 v96, v198
	v_add_f32_e32 v90, v88, v82
	v_add_f32_e32 v91, v89, v83
	s_waitcnt vmcnt(4)
	v_cvt_f32_f16_sdwa v73, v201 dst_sel:DWORD dst_unused:UNUSED_PAD src0_sel:WORD_1
	v_cvt_f32_f16_e32 v72, v201
	v_add_f32_e32 v92, v90, v84
	v_add_f32_e32 v93, v91, v85
	s_waitcnt vmcnt(2)
	v_cvt_f32_f16_sdwa v67, v216 dst_sel:DWORD dst_unused:UNUSED_PAD src0_sel:WORD_1
	v_cvt_f32_f16_e32 v66, v216
	v_add_f32_e32 v98, v92, v94
	v_add_f32_e32 v99, v93, v95
	v_and_or_b32 v68, v169, 64, v153
	v_add_f32_e32 v100, v98, v96
	v_add_f32_e32 v101, v99, v97
	v_lshlrev_b32_e32 v105, 2, v68
	v_add_f32_e32 v102, v100, v72
	v_add_f32_e32 v103, v101, v73
	v_exp_f32_e32 v78, v78
	v_add_f32_e32 v70, v102, v66
	v_add_f32_e32 v71, v103, v67
	ds_bpermute_b32 v68, v105, v70
	ds_bpermute_b32 v69, v105, v71
	ds_bpermute_b32 v74, v105, v70 offset:64
	ds_bpermute_b32 v75, v105, v71 offset:64
	ds_bpermute_b32 v76, v105, v70 offset:128
	ds_bpermute_b32 v77, v105, v71 offset:128
	ds_bpermute_b32 v104, v105, v70 offset:192
	ds_bpermute_b32 v105, v105, v71 offset:192
	s_waitcnt lgkmcnt(6)
	v_cndmask_b32_e64 v107, 0, v69, s[6:7]
	v_cndmask_b32_e64 v106, 0, v68, s[6:7]
	s_waitcnt lgkmcnt(4)
	v_cndmask_b32_e64 v109, 0, v75, s[8:9]
	v_cndmask_b32_e64 v108, 0, v74, s[8:9]
	v_add_f32_e32 v106, v106, v108
	v_add_f32_e32 v107, v107, v109
	s_waitcnt lgkmcnt(2)
	v_cndmask_b32_e64 v109, 0, v77, s[10:11]
	v_cndmask_b32_e64 v108, 0, v76, s[10:11]
	v_add_f32_e32 v106, v106, v108
	v_add_f32_e32 v107, v107, v109
	v_add_f32_e32 v108, v68, v74
	v_add_f32_e32 v109, v69, v75
	v_exp_f32_e32 v79, v79
	v_add_f32_e32 v68, v108, v76
	v_add_f32_e32 v69, v109, v77
	v_exp_f32_e32 v74, v108
	s_waitcnt lgkmcnt(0)
	v_add_f32_e32 v68, v68, v104
	v_add_f32_e32 v69, v69, v105
	v_sub_f32_e32 v104, v106, v108
	v_sub_f32_e32 v105, v107, v109
	v_exp_f32_e32 v75, v109
	v_add_f32_e32 v86, v86, v104
	v_add_f32_e32 v87, v87, v105
	v_sub_f32_e32 v76, v68, v108
	v_sub_f32_e32 v77, v69, v109
	v_exp_f32_e32 v106, v86
	v_exp_f32_e32 v107, v87
	v_exp_f32_e64 v86, -v86
	v_exp_f32_e64 v87, -v87
	v_exp_f32_e32 v76, v76
	v_exp_f32_e32 v77, v77
	v_lshlrev_b32_e32 v108, 16, v183
	v_and_b32_e32 v109, 0xffff0000, v183
	v_sub_f32_e32 v78, 1.0, v78
	v_sub_f32_e32 v79, 1.0, v79
	v_mul_f32_e32 v106, v106, v108
	v_mul_f32_e32 v107, v107, v109
	v_mul_f32_e32 v78, v78, v86
	v_mul_f32_e32 v79, v79, v87
	v_mul_f32_e32 v86, v74, v106
	v_mul_f32_e32 v87, v75, v107
	v_mul_f32_e32 v108, v76, v78
	v_mul_f32_e32 v109, v77, v79
	v_cvt_pk_bf16_f32 v106, v106, v107
	v_cvt_pk_bf16_f32 v86, v86, v87
	v_cvt_pk_bf16_f32 v78, v78, v79
	s_waitcnt vmcnt(0)
	ds_write_b128 v207, v[134:137] offset:36096
	ds_write_b128 v207, v[130:133] offset:36112
	ds_write_b32 v208, v106
	ds_write_b32 v209, v86 offset:8704
	ds_write_b32 v208, v78 offset:17152
	v_cvt_pk_bf16_f32 v78, v108, v109
	ds_write_b32 v210, v78 offset:25856
	v_add_f32_e32 v78, v88, v104
	v_add_f32_e32 v79, v89, v105
	v_exp_f32_e32 v80, v80
	v_exp_f32_e32 v81, v81
	v_exp_f32_e32 v86, v78
	v_exp_f32_e32 v87, v79
	v_exp_f32_e64 v78, -v78
	v_exp_f32_e64 v79, -v79
	v_sub_f32_e32 v80, 1.0, v80
	v_sub_f32_e32 v81, 1.0, v81
	v_lshlrev_b32_e32 v88, 16, v185
	v_and_b32_e32 v89, 0xffff0000, v185
	v_mul_f32_e32 v86, v86, v88
	v_mul_f32_e32 v87, v87, v89
	v_mul_f32_e32 v78, v80, v78
	v_mul_f32_e32 v79, v81, v79
	v_mul_f32_e32 v80, v74, v86
	v_mul_f32_e32 v81, v75, v87
	v_mul_f32_e32 v88, v76, v78
	v_mul_f32_e32 v89, v77, v79
	v_cvt_pk_bf16_f32 v86, v86, v87
	v_cvt_pk_bf16_f32 v78, v78, v79
	v_cvt_pk_bf16_f32 v80, v80, v81
	ds_write2st64_b32 v211, v86, v78 offset1:67
	v_cvt_pk_bf16_f32 v78, v88, v89
	ds_write_b32 v212, v80 offset:8704
	ds_write_b32 v213, v78 offset:25856
	v_add_f32_e32 v78, v90, v104
	v_add_f32_e32 v79, v91, v105
	v_exp_f32_e32 v82, v82
	v_exp_f32_e32 v80, v78
	v_exp_f32_e32 v83, v83
	v_exp_f32_e32 v81, v79
	v_exp_f32_e64 v78, -v78
	v_exp_f32_e64 v79, -v79
	v_lshlrev_b32_e32 v86, 16, v187
	v_and_b32_e32 v87, 0xffff0000, v187
	v_sub_f32_e32 v82, 1.0, v82
	v_sub_f32_e32 v83, 1.0, v83
	v_mul_f32_e32 v80, v80, v86
	v_mul_f32_e32 v81, v81, v87
	v_mul_f32_e32 v78, v82, v78
	v_mul_f32_e32 v79, v83, v79
	v_mul_f32_e32 v82, v74, v80
	v_mul_f32_e32 v83, v75, v81
	v_mul_f32_e32 v86, v76, v78
	v_mul_f32_e32 v87, v77, v79
	v_cvt_pk_bf16_f32 v89, v82, v83
	v_cvt_pk_bf16_f32 v90, v78, v79
	v_add_f32_e32 v78, v92, v104
	v_add_f32_e32 v79, v93, v105
	v_exp_f32_e32 v82, v84
	v_exp_f32_e32 v83, v85
	v_cvt_pk_bf16_f32 v88, v80, v81
	v_exp_f32_e32 v80, v78
	v_exp_f32_e32 v81, v79
	v_exp_f32_e64 v78, -v78
	v_exp_f32_e64 v79, -v79
	v_sub_f32_e32 v82, 1.0, v82
	v_sub_f32_e32 v83, 1.0, v83
	v_lshlrev_b32_e32 v84, 16, v189
	v_and_b32_e32 v85, 0xffff0000, v189
	v_mul_f32_e32 v80, v80, v84
	v_mul_f32_e32 v81, v81, v85
	v_mul_f32_e32 v78, v82, v78
	v_mul_f32_e32 v79, v83, v79
	v_cvt_pk_bf16_f32 v86, v86, v87
	v_mul_f32_e32 v82, v74, v80
	v_mul_f32_e32 v83, v75, v81
	v_mul_f32_e32 v84, v76, v78
	v_mul_f32_e32 v85, v77, v79
	v_cvt_pk_bf16_f32 v80, v80, v81
	v_cvt_pk_bf16_f32 v78, v78, v79
	v_add_u32_e32 v87, 0x4400, v211
	ds_write2_b32 v211, v88, v80 offset0:68 offset1:136
	v_cvt_pk_bf16_f32 v80, v82, v83
	v_add_u32_e32 v81, 0x2200, v212
	ds_write2_b32 v87, v90, v78 offset0:4 offset1:72
	v_cvt_pk_bf16_f32 v78, v84, v85
	v_add_u32_e32 v79, 0x6400, v213
	ds_write2_b32 v81, v89, v80 offset0:66 offset1:132
	ds_write2_b32 v79, v86, v78 offset0:144 offset1:224
	v_add_f32_e32 v78, v98, v104
	v_add_f32_e32 v79, v99, v105
	v_exp_f32_e32 v82, v94
	v_exp_f32_e32 v80, v78
	v_exp_f32_e32 v83, v95
	v_exp_f32_e32 v81, v79
	v_exp_f32_e64 v78, -v78
	v_exp_f32_e64 v79, -v79
	v_lshlrev_b32_e32 v84, 16, v192
	v_and_b32_e32 v85, 0xffff0000, v192
	v_sub_f32_e32 v82, 1.0, v82
	v_sub_f32_e32 v83, 1.0, v83
	v_mul_f32_e32 v80, v80, v84
	v_mul_f32_e32 v81, v81, v85
	v_mul_f32_e32 v78, v82, v78
	v_mul_f32_e32 v79, v83, v79
	v_mul_f32_e32 v82, v74, v80
	v_mul_f32_e32 v83, v75, v81
	v_mul_f32_e32 v84, v76, v78
	v_mul_f32_e32 v85, v77, v79
	v_cvt_pk_bf16_f32 v88, v82, v83
	v_cvt_pk_bf16_f32 v89, v78, v79
	v_add_f32_e32 v78, v100, v104
	v_add_f32_e32 v79, v101, v105
	v_exp_f32_e32 v82, v96
	v_exp_f32_e32 v83, v97
	v_cvt_pk_bf16_f32 v86, v80, v81
	v_exp_f32_e32 v80, v78
	v_exp_f32_e32 v81, v79
	v_exp_f32_e64 v78, -v78
	v_exp_f32_e64 v79, -v79
	v_cvt_pk_bf16_f32 v90, v84, v85
	v_sub_f32_e32 v82, 1.0, v82
	v_sub_f32_e32 v83, 1.0, v83
	v_lshlrev_b32_e32 v84, 16, v197
	v_and_b32_e32 v85, 0xffff0000, v197
	v_mul_f32_e32 v80, v80, v84
	v_mul_f32_e32 v81, v81, v85
	v_mul_f32_e32 v78, v82, v78
	v_mul_f32_e32 v79, v83, v79
	v_mul_f32_e32 v82, v74, v80
	v_mul_f32_e32 v83, v75, v81
	v_mul_f32_e32 v84, v76, v78
	v_mul_f32_e32 v85, v77, v79
	v_cvt_pk_bf16_f32 v80, v80, v81
	v_add_u32_e32 v81, 0x200, v211
	v_cvt_pk_bf16_f32 v78, v78, v79
	ds_write2_b32 v81, v86, v80 offset0:76 offset1:144
	v_cvt_pk_bf16_f32 v80, v82, v83
	v_add_u32_e32 v81, 0x2400, v212
	ds_write2_b32 v87, v89, v78 offset0:140 offset1:208
	v_cvt_pk_bf16_f32 v78, v84, v85
	v_add_u32_e32 v79, 0x6800, v213
	ds_write2_b32 v81, v88, v80 offset0:70 offset1:136
	ds_write2_b32 v79, v90, v78 offset0:48 offset1:128
	v_add_f32_e32 v78, v102, v104
	v_add_f32_e32 v79, v103, v105
	v_exp_f32_e32 v72, v72
	v_exp_f32_e32 v73, v73
	v_exp_f32_e32 v80, v78
	v_exp_f32_e32 v81, v79
	v_exp_f32_e64 v78, -v78
	v_exp_f32_e64 v79, -v79
	v_sub_f32_e32 v72, 1.0, v72
	v_sub_f32_e32 v73, 1.0, v73
	v_lshlrev_b32_e32 v82, 16, v200
	v_and_b32_e32 v83, 0xffff0000, v200
	v_mul_f32_e32 v80, v80, v82
	v_mul_f32_e32 v81, v81, v83
	v_mul_f32_e32 v72, v72, v78
	v_mul_f32_e32 v73, v73, v79
	v_add_f32_e32 v70, v70, v104
	v_add_f32_e32 v71, v71, v105
	v_exp_f32_e32 v66, v66
	v_exp_f32_e32 v67, v67
	v_mul_f32_e32 v78, v74, v80
	v_mul_f32_e32 v79, v75, v81
	v_mul_f32_e32 v82, v76, v72
	v_mul_f32_e32 v83, v77, v73
	v_cvt_pk_bf16_f32 v80, v80, v81
	v_cvt_pk_bf16_f32 v81, v72, v73
	v_exp_f32_e32 v72, v70
	v_exp_f32_e32 v73, v71
	v_exp_f32_e64 v70, -v70
	v_exp_f32_e64 v71, -v71
	v_cvt_pk_bf16_f32 v78, v78, v79
	ds_write_b32 v212, v78 offset:10024
	v_sub_f32_e32 v66, 1.0, v66
	v_sub_f32_e32 v67, 1.0, v67
	v_lshlrev_b32_e32 v78, 16, v214
	v_and_b32_e32 v79, 0xffff0000, v214
	v_mul_f32_e32 v72, v72, v78
	v_mul_f32_e32 v73, v73, v79
	v_mul_f32_e32 v66, v66, v70
	v_mul_f32_e32 v67, v67, v71
	v_mul_f32_e32 v70, v74, v72
	v_mul_f32_e32 v71, v75, v73
	v_mul_f32_e32 v74, v76, v66
	v_mul_f32_e32 v75, v77, v67
	v_cvt_pk_bf16_f32 v66, v66, v67
	v_add_u32_e32 v67, 0x4800, v211
	v_cvt_pk_bf16_f32 v82, v82, v83
	v_cvt_pk_bf16_f32 v72, v72, v73
	v_add_u32_e32 v73, 0x400, v211
	v_cvt_pk_bf16_f32 v70, v70, v71
	ds_write2_b32 v67, v81, v66 offset0:20 offset1:88
	v_cvt_pk_bf16_f32 v66, v74, v75
	v_add_u32_e32 v67, 0x6a00, v213
	ds_write2_b32 v73, v80, v72 offset0:84 offset1:152
	ds_write_b32 v212, v70 offset:10288
	ds_write2_b32 v67, v82, v66 offset0:80 offset1:160
	s_and_saveexec_b64 s[14:15], s[12:13]
	s_cbranch_execz .LBB0_1344
	v_exp_f32_e32 v66, v68
	v_exp_f32_e32 v67, v69
	ds_write_b64 v215, v[66:67] offset:46336
